# attention epilogues: 40 dwordx2 output stores paired via v_permlane32_swap into 20 dwordx4 stores (docs 7.3); on top of v14
# speedup vs baseline: 1.0108x; 1.0108x over previous
.LBB0_308:
	s_waitcnt lgkmcnt(0)
	v_add_f32_e32 v0, v0, v36
	v_div_scale_f32 v36, s[0:1], v0, v0, 1.0
	v_rcp_f32_e32 v37, v36
	v_div_scale_f32 v38, vcc, 1.0, v0, 1.0
	v_fma_f32 v39, -v36, v37, 1.0
	v_fmac_f32_e32 v37, v39, v37
	v_mul_f32_e32 v39, v38, v37
	v_fma_f32 v40, -v36, v39, v38
	v_fmac_f32_e32 v39, v40, v37
	v_fma_f32 v36, -v36, v39, v38
	v_div_fmas_f32 v36, v36, v37, v39
	v_div_fixup_f32 v36, v36, v0, 1.0
	v_lshlrev_b32_e32 v0, 3, v149
	v_pk_mul_f32 v[2:3], v[36:37], v[2:3] op_sel_hi:[0,1]
	v_pk_mul_f32 v[4:5], v[36:37], v[4:5] op_sel_hi:[0,1]
	v_lshl_add_u64 v[34:35], v[34:35], 0, v[0:1]
	v_mbcnt_lo_u32_b32 v236, -1, 0
	v_mbcnt_hi_u32_b32 v236, -1, v236
	v_and_b32_e32 v236, 32, v236
	v_lshrrev_b32_e32 v236, 2, v236
	v_mov_b32_e32 v237, 0
	v_lshl_add_u64 v[34:35], v[34:35], 0, v[236:237]
	v_cvt_pk_bf16_f32 v220, v2, v3
	v_cvt_pk_bf16_f32 v221, v4, v5
	v_pk_mul_f32 v[2:3], v[36:37], v[6:7] op_sel_hi:[0,1]
	v_pk_mul_f32 v[4:5], v[36:37], v[8:9] op_sel_hi:[0,1]
	v_cvt_pk_bf16_f32 v222, v2, v3
	v_cvt_pk_bf16_f32 v223, v4, v5
	s_nop 1
	v_permlane32_swap_b32_e32 v220, v222
	v_permlane32_swap_b32_e32 v221, v223
	global_store_dwordx4 v[34:35], v[220:223], off
	v_pk_mul_f32 v[2:3], v[36:37], v[10:11] op_sel_hi:[0,1]
	v_pk_mul_f32 v[4:5], v[36:37], v[12:13] op_sel_hi:[0,1]
	v_cvt_pk_bf16_f32 v224, v2, v3
	v_cvt_pk_bf16_f32 v225, v4, v5
	v_pk_mul_f32 v[2:3], v[36:37], v[14:15] op_sel_hi:[0,1]
	v_pk_mul_f32 v[4:5], v[36:37], v[16:17] op_sel_hi:[0,1]
	v_cvt_pk_bf16_f32 v226, v2, v3
	v_cvt_pk_bf16_f32 v227, v4, v5
	s_nop 1
	v_permlane32_swap_b32_e32 v224, v226
	v_permlane32_swap_b32_e32 v225, v227
	global_store_dwordx4 v[34:35], v[224:227], off offset:32
	v_pk_mul_f32 v[2:3], v[36:37], v[18:19] op_sel_hi:[0,1]
	v_pk_mul_f32 v[4:5], v[36:37], v[20:21] op_sel_hi:[0,1]
	v_cvt_pk_bf16_f32 v228, v2, v3
	v_cvt_pk_bf16_f32 v229, v4, v5
	v_pk_mul_f32 v[2:3], v[36:37], v[22:23] op_sel_hi:[0,1]
	v_pk_mul_f32 v[4:5], v[36:37], v[24:25] op_sel_hi:[0,1]
	v_cvt_pk_bf16_f32 v230, v2, v3
	v_cvt_pk_bf16_f32 v231, v4, v5
	s_nop 1
	v_permlane32_swap_b32_e32 v228, v230
	v_permlane32_swap_b32_e32 v229, v231
	global_store_dwordx4 v[34:35], v[228:231], off offset:64
	v_pk_mul_f32 v[2:3], v[36:37], v[26:27] op_sel_hi:[0,1]
	v_pk_mul_f32 v[4:5], v[36:37], v[28:29] op_sel_hi:[0,1]
	v_cvt_pk_bf16_f32 v232, v2, v3
	v_cvt_pk_bf16_f32 v233, v4, v5
	v_pk_mul_f32 v[2:3], v[36:37], v[30:31] op_sel_hi:[0,1]
	v_pk_mul_f32 v[4:5], v[36:37], v[32:33] op_sel_hi:[0,1]
	v_cvt_pk_bf16_f32 v234, v2, v3
	v_cvt_pk_bf16_f32 v235, v4, v5
	s_nop 1
	v_permlane32_swap_b32_e32 v232, v234
	v_permlane32_swap_b32_e32 v233, v235
	global_store_dwordx4 v[34:35], v[232:235], off offset:96
	s_load_dword s0, s[84:85], 0x10
	s_waitcnt lgkmcnt(0)
	s_lshr_b32 s0, s0, 16
	s_cmp_lg_u32 s0, 0
	s_cselect_b64 s[0:1], -1, 0
	s_cmp_lg_u64 s[0:1], 0
	v_readlane_b32 s0, v244, 0
	s_addc_u32 s2, s2, s0
	s_cmpk_gt_i32 s2, 0x9ff
	v_readlane_b32 s1, v244, 1
	s_cbranch_scc1 .LBB0_341

.LBB0_345:
	v_add_u32_e32 v0, s13, v177
	ds_read_b128 v[38:41], v0 offset:13312
	ds_read_b128 v[42:45], v0 offset:13344
	v_lshlrev_b64 v[34:35], 11, v[118:119]
	v_lshl_add_u64 v[34:35], s[46:47], 0, v[34:35]
	v_lshl_add_u64 v[46:47], s[4:5], 1, v[34:35]
	v_cvt_pk_bf16_f32 v34, v136, v137
	v_cvt_pk_bf16_f32 v35, v134, v135
	v_cvt_pk_bf16_f32 v36, v132, v133
	v_cvt_pk_bf16_f32 v37, v138, v139
	s_waitcnt lgkmcnt(1)
	s_nop 0
	v_mfma_f32_32x32x16_bf16 v[18:33], v[38:41], v[34:37], v[18:33]
	ds_read_b128 v[38:41], v0 offset:15872
	s_waitcnt lgkmcnt(0)
	v_mfma_f32_32x32x16_bf16 v[2:17], v[38:41], v[34:37], v[2:17]
	ds_read_b128 v[38:41], v0 offset:15904
	v_cvt_pk_bf16_f32 v34, v152, v153
	v_cvt_pk_bf16_f32 v35, v150, v151
	v_cvt_pk_bf16_f32 v36, v156, v157
	v_cvt_pk_bf16_f32 v37, v160, v161
	s_waitcnt lgkmcnt(0)
	s_nop 0
	v_mfma_f32_32x32x16_bf16 v[2:17], v[38:41], v[34:37], v[2:17]
	ds_read_b128 v[38:41], v0 offset:18432
	v_mfma_f32_32x32x16_bf16 v[18:33], v[42:45], v[34:37], v[18:33]
	v_cvt_pk_bf16_f32 v34, v148, v149
	v_cvt_pk_bf16_f32 v35, v140, v141
	v_cvt_pk_bf16_f32 v36, v154, v155
	v_cvt_pk_bf16_f32 v37, v158, v159
	s_waitcnt lgkmcnt(0)
	s_nop 0
	v_mfma_f32_32x32x16_bf16 v[18:33], v[38:41], v[34:37], v[18:33]
	ds_read_b128 v[38:41], v0 offset:20992
	s_waitcnt lgkmcnt(0)
	v_mfma_f32_32x32x16_bf16 v[2:17], v[38:41], v[34:37], v[2:17]
	ds_read_b128 v[38:41], v0 offset:18464
	v_cvt_pk_bf16_f32 v34, v162, v163
	v_cvt_pk_bf16_f32 v35, v164, v165
	v_cvt_pk_bf16_f32 v36, v166, v167
	v_cvt_pk_bf16_f32 v37, v168, v169
	s_waitcnt lgkmcnt(0)
	s_nop 0
	v_mfma_f32_32x32x16_bf16 v[18:33], v[38:41], v[34:37], v[18:33]
	ds_read_b128 v[38:41], v0 offset:21024
	v_add_f32_e32 v0, 0, v136
	v_add_f32_e32 v0, v0, v137
	v_add_f32_e32 v0, v0, v134
	v_add_f32_e32 v0, v0, v135
	v_add_f32_e32 v0, v0, v132
	v_add_f32_e32 v0, v0, v133
	v_add_f32_e32 v0, v0, v138
	v_add_f32_e32 v0, v0, v139
	v_add_f32_e32 v0, v0, v152
	v_add_f32_e32 v0, v0, v153
	v_add_f32_e32 v0, v0, v150
	v_add_f32_e32 v0, v0, v151
	v_add_f32_e32 v0, v0, v156
	v_add_f32_e32 v0, v0, v157
	v_add_f32_e32 v0, v0, v160
	v_add_f32_e32 v0, v0, v161
	v_add_f32_e32 v0, v0, v148
	v_add_f32_e32 v0, v0, v149
	v_add_f32_e32 v0, v0, v140
	v_add_f32_e32 v0, v0, v141
	v_add_f32_e32 v0, v0, v154
	v_add_f32_e32 v0, v0, v155
	v_add_f32_e32 v0, v0, v158
	v_add_f32_e32 v0, v0, v159
	v_add_f32_e32 v0, v0, v162
	v_add_f32_e32 v0, v0, v163
	v_add_f32_e32 v0, v0, v164
	v_add_f32_e32 v0, v0, v165
	v_add_f32_e32 v0, v0, v166
	v_add_f32_e32 v0, v0, v167
	v_add_f32_e32 v0, v0, v168
	v_add_f32_e32 v0, v0, v169
	v_add_f32_e32 v0, v174, v0
	s_waitcnt lgkmcnt(0)
	v_mfma_f32_32x32x16_bf16 v[2:17], v[38:41], v[34:37], v[2:17]
	ds_bpermute_b32 v34, v125, v0
	s_waitcnt lgkmcnt(0)
	v_add_f32_e32 v0, v0, v34
	v_div_scale_f32 v34, s[0:1], v0, v0, 1.0
	v_rcp_f32_e32 v35, v34
	s_nop 0
	v_fma_f32 v36, -v34, v35, 1.0
	v_fmac_f32_e32 v35, v36, v35
	v_div_scale_f32 v36, vcc, 1.0, v0, 1.0
	v_mul_f32_e32 v37, v36, v35
	v_fma_f32 v38, -v34, v37, v36
	v_fmac_f32_e32 v37, v38, v35
	v_fma_f32 v34, -v34, v37, v36
	v_div_fmas_f32 v34, v34, v35, v37
	v_div_fixup_f32 v34, v34, v0, 1.0
	v_lshlrev_b32_e32 v0, 3, v171
	v_pk_mul_f32 v[18:19], v[18:19], v[34:35] op_sel_hi:[1,0]
	v_pk_mul_f32 v[20:21], v[20:21], v[34:35] op_sel_hi:[1,0]
	v_pk_mul_f32 v[2:3], v[2:3], v[34:35] op_sel_hi:[1,0]
	v_pk_mul_f32 v[4:5], v[4:5], v[34:35] op_sel_hi:[1,0]
	v_lshl_add_u64 v[36:37], v[46:47], 0, v[0:1]
	v_mbcnt_lo_u32_b32 v236, -1, 0
	v_mbcnt_hi_u32_b32 v236, -1, v236
	v_and_b32_e32 v236, 32, v236
	v_lshrrev_b32_e32 v236, 2, v236
	v_mov_b32_e32 v237, 0
	v_lshl_add_u64 v[36:37], v[36:37], 0, v[236:237]
	v_cvt_pk_bf16_f32 v220, v18, v19
	v_cvt_pk_bf16_f32 v221, v20, v21
	v_cvt_pk_bf16_f32 v228, v2, v3
	v_cvt_pk_bf16_f32 v229, v4, v5
	v_pk_mul_f32 v[18:19], v[22:23], v[34:35] op_sel_hi:[1,0]
	v_pk_mul_f32 v[20:21], v[24:25], v[34:35] op_sel_hi:[1,0]
	v_pk_mul_f32 v[2:3], v[6:7], v[34:35] op_sel_hi:[1,0]
	v_pk_mul_f32 v[4:5], v[8:9], v[34:35] op_sel_hi:[1,0]
	v_cvt_pk_bf16_f32 v222, v18, v19
	v_cvt_pk_bf16_f32 v223, v20, v21
	v_cvt_pk_bf16_f32 v230, v2, v3
	v_cvt_pk_bf16_f32 v231, v4, v5
	s_nop 1
	v_permlane32_swap_b32_e32 v220, v222
	v_permlane32_swap_b32_e32 v221, v223
	global_store_dwordx4 v[36:37], v[220:223], off
	v_pk_mul_f32 v[18:19], v[26:27], v[34:35] op_sel_hi:[1,0]
	v_pk_mul_f32 v[20:21], v[28:29], v[34:35] op_sel_hi:[1,0]
	s_nop 1
	v_permlane32_swap_b32_e32 v228, v230
	v_permlane32_swap_b32_e32 v229, v231
	global_store_dwordx4 v[36:37], v[228:231], off offset:64
	v_pk_mul_f32 v[2:3], v[10:11], v[34:35] op_sel_hi:[1,0]
	v_pk_mul_f32 v[4:5], v[12:13], v[34:35] op_sel_hi:[1,0]
	v_cvt_pk_bf16_f32 v224, v18, v19
	v_cvt_pk_bf16_f32 v225, v20, v21
	v_cvt_pk_bf16_f32 v232, v2, v3
	v_cvt_pk_bf16_f32 v233, v4, v5
	v_pk_mul_f32 v[18:19], v[30:31], v[34:35] op_sel_hi:[1,0]
	v_pk_mul_f32 v[20:21], v[32:33], v[34:35] op_sel_hi:[1,0]
	v_pk_mul_f32 v[2:3], v[14:15], v[34:35] op_sel_hi:[1,0]
	v_pk_mul_f32 v[4:5], v[16:17], v[34:35] op_sel_hi:[1,0]
	v_cvt_pk_bf16_f32 v226, v18, v19
	v_cvt_pk_bf16_f32 v227, v20, v21
	v_cvt_pk_bf16_f32 v234, v2, v3
	v_cvt_pk_bf16_f32 v235, v4, v5
	s_nop 1
	v_permlane32_swap_b32_e32 v224, v226
	v_permlane32_swap_b32_e32 v225, v227
	global_store_dwordx4 v[36:37], v[224:227], off offset:32
	s_nop 1
	v_permlane32_swap_b32_e32 v232, v234
	v_permlane32_swap_b32_e32 v233, v235
	global_store_dwordx4 v[36:37], v[232:235], off offset:96
	s_load_dword s0, s[84:85], 0x10
	s_waitcnt lgkmcnt(0)
	s_lshr_b32 s0, s0, 16
	s_cmp_lg_u32 s0, 0
	s_cselect_b64 s[0:1], -1, 0
	s_cmp_lg_u64 s[0:1], 0
	v_readlane_b32 s0, v244, 0
	s_addc_u32 s2, s2, s0
	s_cmpk_gt_i32 s2, 0x9ff
	v_readlane_b32 s1, v244, 1
	s_cbranch_scc1 .LBB0_373

.LBB0_379:
	s_waitcnt lgkmcnt(0)
	v_add_f32_e32 v0, v0, v36
	v_div_scale_f32 v36, s[0:1], v0, v0, 1.0
	v_rcp_f32_e32 v37, v36
	v_div_scale_f32 v38, vcc, 1.0, v0, 1.0
	v_fma_f32 v39, -v36, v37, 1.0
	v_fmac_f32_e32 v37, v39, v37
	v_mul_f32_e32 v39, v38, v37
	v_fma_f32 v40, -v36, v39, v38
	v_fmac_f32_e32 v39, v40, v37
	v_fma_f32 v36, -v36, v39, v38
	v_div_fmas_f32 v36, v36, v37, v39
	v_div_fixup_f32 v36, v36, v0, 1.0
	v_lshlrev_b32_e32 v0, 3, v153
	v_pk_mul_f32 v[2:3], v[36:37], v[2:3] op_sel_hi:[0,1]
	v_pk_mul_f32 v[4:5], v[36:37], v[4:5] op_sel_hi:[0,1]
	v_lshl_add_u64 v[34:35], v[34:35], 0, v[0:1]
	v_mbcnt_lo_u32_b32 v236, -1, 0
	v_mbcnt_hi_u32_b32 v236, -1, v236
	v_and_b32_e32 v236, 32, v236
	v_lshrrev_b32_e32 v236, 2, v236
	v_mov_b32_e32 v237, 0
	v_lshl_add_u64 v[34:35], v[34:35], 0, v[236:237]
	v_cvt_pk_bf16_f32 v220, v2, v3
	v_cvt_pk_bf16_f32 v221, v4, v5
	v_pk_mul_f32 v[2:3], v[36:37], v[6:7] op_sel_hi:[0,1]
	v_pk_mul_f32 v[4:5], v[36:37], v[8:9] op_sel_hi:[0,1]
	v_cvt_pk_bf16_f32 v222, v2, v3
	v_cvt_pk_bf16_f32 v223, v4, v5
	s_nop 1
	v_permlane32_swap_b32_e32 v220, v222
	v_permlane32_swap_b32_e32 v221, v223
	global_store_dwordx4 v[34:35], v[220:223], off
	v_pk_mul_f32 v[2:3], v[36:37], v[10:11] op_sel_hi:[0,1]
	v_pk_mul_f32 v[4:5], v[36:37], v[12:13] op_sel_hi:[0,1]
	v_cvt_pk_bf16_f32 v224, v2, v3
	v_cvt_pk_bf16_f32 v225, v4, v5
	v_pk_mul_f32 v[2:3], v[36:37], v[14:15] op_sel_hi:[0,1]
	v_pk_mul_f32 v[4:5], v[36:37], v[16:17] op_sel_hi:[0,1]
	v_cvt_pk_bf16_f32 v226, v2, v3
	v_cvt_pk_bf16_f32 v227, v4, v5
	s_nop 1
	v_permlane32_swap_b32_e32 v224, v226
	v_permlane32_swap_b32_e32 v225, v227
	global_store_dwordx4 v[34:35], v[224:227], off offset:32
	v_pk_mul_f32 v[2:3], v[36:37], v[18:19] op_sel_hi:[0,1]
	v_pk_mul_f32 v[4:5], v[36:37], v[20:21] op_sel_hi:[0,1]
	v_cvt_pk_bf16_f32 v228, v2, v3
	v_cvt_pk_bf16_f32 v229, v4, v5
	v_pk_mul_f32 v[2:3], v[36:37], v[22:23] op_sel_hi:[0,1]
	v_pk_mul_f32 v[4:5], v[36:37], v[24:25] op_sel_hi:[0,1]
	v_cvt_pk_bf16_f32 v230, v2, v3
	v_cvt_pk_bf16_f32 v231, v4, v5
	s_nop 1
	v_permlane32_swap_b32_e32 v228, v230
	v_permlane32_swap_b32_e32 v229, v231
	global_store_dwordx4 v[34:35], v[228:231], off offset:64
	v_pk_mul_f32 v[2:3], v[36:37], v[26:27] op_sel_hi:[0,1]
	v_pk_mul_f32 v[4:5], v[36:37], v[28:29] op_sel_hi:[0,1]
	v_cvt_pk_bf16_f32 v232, v2, v3
	v_cvt_pk_bf16_f32 v233, v4, v5
	v_pk_mul_f32 v[2:3], v[36:37], v[30:31] op_sel_hi:[0,1]
	v_pk_mul_f32 v[4:5], v[36:37], v[32:33] op_sel_hi:[0,1]
	v_cvt_pk_bf16_f32 v234, v2, v3
	v_cvt_pk_bf16_f32 v235, v4, v5
	s_nop 1
	v_permlane32_swap_b32_e32 v232, v234
	v_permlane32_swap_b32_e32 v233, v235
	global_store_dwordx4 v[34:35], v[232:235], off offset:96
	s_load_dword s0, s[84:85], 0x10
	s_waitcnt lgkmcnt(0)
	s_lshr_b32 s0, s0, 16
	s_cmp_lg_u32 s0, 0
	s_cselect_b64 s[0:1], -1, 0
	s_cmp_lg_u64 s[0:1], 0
	v_readlane_b32 s0, v244, 0
	s_addc_u32 s2, s2, s0
	s_cmpk_gt_i32 s2, 0x9ff
	v_readlane_b32 s1, v244, 1
	s_cbranch_scc1 .LBB0_434

.LBB0_438:
	v_add_u32_e32 v0, s11, v211
	ds_read_b128 v[66:69], v0 offset:9216
	v_cvt_pk_bf16_f32 v70, v156, v157
	v_cvt_pk_bf16_f32 v71, v158, v159
	v_cvt_pk_bf16_f32 v72, v160, v161
	v_cvt_pk_bf16_f32 v73, v162, v163
	v_lshl_add_u64 v[74:75], v[148:149], 1, s[46:47]
	v_lshl_add_u64 v[78:79], s[0:1], 1, v[74:75]
	v_cvt_pk_bf16_f32 v84, v164, v165
	v_cvt_pk_bf16_f32 v85, v168, v169
	s_waitcnt lgkmcnt(0)
	v_mfma_f32_32x32x16_bf16 v[2:17], v[66:69], v[70:73], v[2:17]
	ds_read_b128 v[66:69], v0 offset:11776
	ds_read_b128 v[74:77], v0 offset:9248
	ds_read_b128 v[80:83], v0 offset:14336
	v_cvt_pk_bf16_f32 v86, v172, v173
	v_cvt_pk_bf16_f32 v87, v176, v177
	v_cvt_pk_bf16_f32 v96, v166, v167
	v_cvt_pk_bf16_f32 v97, v170, v171
	v_cvt_pk_bf16_f32 v98, v174, v175
	s_waitcnt lgkmcnt(0)
	v_mfma_f32_32x32x16_bf16 v[34:49], v[80:83], v[70:73], v[34:49]
	v_cvt_pk_bf16_f32 v99, v178, v179
	s_waitcnt vmcnt(0)
	v_lshl_add_u32 v122, v206, 2, v192
	v_readlane_b32 s52, v244, 6
	v_readlane_b32 s60, v244, 14
	v_readlane_b32 s61, v244, 15
	v_readlane_b32 s54, v244, 8
	s_mov_b32 s54, 0x800000
	v_mfma_f32_32x32x16_bf16 v[50:65], v[66:69], v[70:73], v[50:65]
	ds_read_b128 v[66:69], v0 offset:16896
	ds_read_b128 v[88:91], v0 offset:11808
	ds_read_b128 v[92:95], v0 offset:14368
	ds_read_b128 v[80:83], v0 offset:16928
	ds_read_b128 v[100:103], v0 offset:19456
	ds_read_b128 v[104:107], v0 offset:22016
	v_readlane_b32 s55, v244, 9
	v_readlane_b32 s56, v244, 10
	v_readlane_b32 s56, v241, 36
	s_waitcnt lgkmcnt(5)
	v_mfma_f32_32x32x16_bf16 v[18:33], v[66:69], v[70:73], v[18:33]
	v_add_f32_e32 v67, 0, v156
	v_add_f32_e32 v67, v67, v157
	v_add_f32_e32 v67, v67, v158
	v_add_f32_e32 v67, v67, v159
	v_add_f32_e32 v67, v67, v160
	v_add_f32_e32 v67, v67, v161
	v_add_f32_e32 v67, v67, v162
	v_add_f32_e32 v67, v67, v163
	v_add_f32_e32 v67, v67, v164
	v_add_f32_e32 v67, v67, v165
	v_add_f32_e32 v67, v67, v168
	v_add_f32_e32 v67, v67, v169
	v_add_f32_e32 v67, v67, v172
	v_add_f32_e32 v67, v67, v173
	v_add_f32_e32 v67, v67, v176
	v_add_f32_e32 v67, v67, v177
	v_add_f32_e32 v67, v67, v166
	v_add_f32_e32 v67, v67, v167
	v_add_f32_e32 v67, v67, v170
	v_add_f32_e32 v67, v67, v171
	v_add_f32_e32 v67, v67, v174
	v_add_f32_e32 v67, v67, v175
	v_add_f32_e32 v67, v67, v178
	v_add_f32_e32 v67, v67, v179
	v_add_f32_e32 v67, v67, v180
	v_add_f32_e32 v67, v67, v181
	v_add_f32_e32 v67, v67, v182
	v_add_f32_e32 v67, v67, v183
	v_add_f32_e32 v67, v67, v184
	v_add_f32_e32 v67, v67, v185
	v_add_f32_e32 v67, v67, v186
	v_add_f32_e32 v67, v67, v187
	s_waitcnt lgkmcnt(2)
	v_mfma_f32_32x32x16_bf16 v[18:33], v[80:83], v[84:87], v[18:33]
	v_add_f32_e32 v80, v209, v67
	ds_bpermute_b32 v81, v190, v80
	ds_read_b128 v[70:73], v0 offset:24576
	ds_read_b128 v[108:111], v0 offset:27136
	v_cvt_pk_bf16_f32 v66, v180, v181
	v_cvt_pk_bf16_f32 v67, v182, v183
	v_cvt_pk_bf16_f32 v68, v184, v185
	v_cvt_pk_bf16_f32 v69, v186, v187
	v_mfma_f32_32x32x16_bf16 v[2:17], v[74:77], v[84:87], v[2:17]
	ds_read_b128 v[74:77], v0 offset:19488
	s_movk_i32 s55, 0x1fff
	v_readlane_b32 s53, v244, 7
	v_readlane_b32 s57, v244, 11
	v_readlane_b32 s58, v244, 12
	v_readlane_b32 s59, v244, 13
	v_readlane_b32 s62, v244, 16
	v_mfma_f32_32x32x16_bf16 v[50:65], v[88:91], v[84:87], v[50:65]
	s_waitcnt lgkmcnt(3)
	v_add_f32_e32 v88, v80, v81
	v_div_scale_f32 v89, s[0:1], v88, v88, 1.0
	v_rcp_f32_e32 v90, v89
	v_readlane_b32 s63, v244, 17
	v_readlane_b32 s64, v244, 18
	v_readlane_b32 s65, v244, 19
	v_mfma_f32_32x32x16_bf16 v[34:49], v[92:95], v[84:87], v[34:49]
	v_readlane_b32 s66, v244, 20
	v_readlane_b32 s67, v244, 21
	v_mfma_f32_32x32x16_bf16 v[2:17], v[100:103], v[96:99], v[2:17]
	ds_read_b128 v[80:83], v0 offset:22048
	ds_read_b128 v[84:87], v0 offset:24608
	ds_read_b128 v[100:103], v0 offset:27168
	v_fma_f32 v0, -v89, v90, 1.0
	v_fmac_f32_e32 v90, v0, v90
	v_div_scale_f32 v0, vcc, 1.0, v88, 1.0
	v_mfma_f32_32x32x16_bf16 v[50:65], v[104:107], v[96:99], v[50:65]
	s_waitcnt lgkmcnt(5)
	v_mfma_f32_32x32x16_bf16 v[34:49], v[70:73], v[96:99], v[34:49]
	v_mul_f32_e32 v70, v0, v90
	v_fma_f32 v71, -v89, v70, v0
	v_fmac_f32_e32 v70, v71, v90
	v_fma_f32 v0, -v89, v70, v0
	v_div_fmas_f32 v0, v0, v90, v70
	ds_read2st64_b32 v[72:73], v122 offset1:1
	v_div_fixup_f32 v0, v0, v88, 1.0
	s_waitcnt lgkmcnt(5)
	v_mfma_f32_32x32x16_bf16 v[18:33], v[108:111], v[96:99], v[18:33]
	ds_read2st64_b32 v[88:89], v122 offset0:2 offset1:3
	v_mul_f32_e32 v0, v191, v0
	s_waitcnt lgkmcnt(5)
	v_mfma_f32_32x32x16_bf16 v[2:17], v[74:77], v[66:69], v[2:17]
	ds_read2st64_b32 v[76:77], v122 offset0:4 offset1:5
	s_waitcnt lgkmcnt(5)
	v_mfma_f32_32x32x16_bf16 v[50:65], v[80:83], v[66:69], v[50:65]
	ds_read2st64_b32 v[80:81], v122 offset0:6 offset1:7
	ds_read2st64_b32 v[82:83], v122 offset0:8 offset1:9
	s_waitcnt lgkmcnt(4)
	v_lshlrev_b32_e32 v70, 16, v72
	v_and_b32_e32 v71, 0xffff0000, v72
	s_waitcnt lgkmcnt(1)
	v_lshlrev_b32_e32 v90, 16, v80
	v_and_b32_e32 v91, 0xffff0000, v80
	v_mfma_f32_32x32x16_bf16 v[34:49], v[84:87], v[66:69], v[34:49]
	v_lshlrev_b32_e32 v106, 16, v81
	v_and_b32_e32 v107, 0xffff0000, v81
	ds_read2st64_b32 v[80:81], v122 offset0:10 offset1:11
	v_lshlrev_b32_e32 v112, 16, v73
	v_and_b32_e32 v113, 0xffff0000, v73
	v_lshlrev_b32_e32 v72, 16, v89
	v_and_b32_e32 v73, 0xffff0000, v89
	v_mfma_f32_32x32x16_bf16 v[18:33], v[100:103], v[66:69], v[18:33]
	ds_read2st64_b32 v[66:67], v122 offset0:12 offset1:13
	ds_read2st64_b32 v[68:69], v122 offset0:14 offset1:15
	s_waitcnt lgkmcnt(2)
	v_lshlrev_b32_e32 v96, 16, v80
	v_and_b32_e32 v97, 0xffff0000, v80
	s_waitcnt lgkmcnt(1)
	v_lshlrev_b32_e32 v92, 16, v66
	v_and_b32_e32 v93, 0xffff0000, v66
	v_lshlrev_b32_e32 v116, 16, v67
	v_and_b32_e32 v117, 0xffff0000, v67
	ds_read2st64_b32 v[66:67], v122 offset0:16 offset1:17
	s_waitcnt lgkmcnt(1)
	v_lshlrev_b32_e32 v108, 16, v68
	v_and_b32_e32 v109, 0xffff0000, v68
	v_lshlrev_b32_e32 v126, 16, v69
	v_and_b32_e32 v127, 0xffff0000, v69
	ds_read2st64_b32 v[68:69], v122 offset0:18 offset1:19
	s_waitcnt lgkmcnt(1)
	v_lshlrev_b32_e32 v98, 16, v66
	v_and_b32_e32 v99, 0xffff0000, v66
	v_lshlrev_b32_e32 v120, 16, v67
	v_and_b32_e32 v121, 0xffff0000, v67
	ds_read2st64_b32 v[66:67], v122 offset0:20 offset1:21
	s_waitcnt lgkmcnt(1)
	v_lshlrev_b32_e32 v110, 16, v68
	v_and_b32_e32 v111, 0xffff0000, v68
	v_lshlrev_b32_e32 v124, 16, v69
	v_and_b32_e32 v125, 0xffff0000, v69
	ds_read2st64_b32 v[68:69], v122 offset0:22 offset1:23
	s_waitcnt lgkmcnt(1)
	v_lshlrev_b32_e32 v100, 16, v66
	v_and_b32_e32 v101, 0xffff0000, v66
	v_lshlrev_b32_e32 v134, 16, v67
	v_and_b32_e32 v135, 0xffff0000, v67
	ds_read2st64_b32 v[66:67], v122 offset0:24 offset1:25
	s_waitcnt lgkmcnt(1)
	v_lshlrev_b32_e32 v130, 16, v68
	v_and_b32_e32 v131, 0xffff0000, v68
	v_lshlrev_b32_e32 v136, 16, v69
	v_and_b32_e32 v137, 0xffff0000, v69
	ds_read2st64_b32 v[68:69], v122 offset0:26 offset1:27
	s_waitcnt lgkmcnt(1)
	v_lshlrev_b32_e32 v114, 16, v66
	v_and_b32_e32 v115, 0xffff0000, v66
	v_lshlrev_b32_e32 v132, 16, v67
	v_and_b32_e32 v133, 0xffff0000, v67
	ds_read2st64_b32 v[66:67], v122 offset0:28 offset1:29
	v_lshlrev_b32_e32 v104, 16, v81
	v_and_b32_e32 v105, 0xffff0000, v81
	s_waitcnt lgkmcnt(1)
	v_lshlrev_b32_e32 v118, 16, v68
	v_and_b32_e32 v119, 0xffff0000, v68
	v_lshlrev_b32_e32 v128, 16, v69
	v_and_b32_e32 v129, 0xffff0000, v69
	s_waitcnt lgkmcnt(0)
	v_lshlrev_b32_e32 v69, 16, v67
	v_lshlrev_b32_e32 v68, 16, v66
	v_mov_b32_e32 v80, v26
	v_mov_b32_e32 v81, v28
	v_pk_fma_f32 v[84:85], v[80:81], v[0:1], v[68:69] op_sel_hi:[1,0,1] neg_lo:[1,0,0] neg_hi:[1,0,0]
	ds_read2st64_b32 v[68:69], v122 offset0:30 offset1:31
	v_and_b32_e32 v67, 0xffff0000, v67
	v_and_b32_e32 v66, 0xffff0000, v66
	v_mov_b32_e32 v28, v27
	v_pk_fma_f32 v[86:87], v[28:29], v[0:1], v[66:67] op_sel_hi:[1,0,1] neg_lo:[1,0,0] neg_hi:[1,0,0]
	v_mov_b32_e32 v28, v30
	v_pk_mul_f32 v[26:27], v[86:87], v[86:87]
	v_mov_b32_e32 v29, v32
	v_pk_fma_f32 v[122:123], v[84:85], v[84:85], v[26:27]
	s_waitcnt lgkmcnt(0)
	v_lshlrev_b32_e32 v27, 16, v69
	v_lshlrev_b32_e32 v26, 16, v68
	v_pk_fma_f32 v[80:81], v[28:29], v[0:1], v[26:27] op_sel_hi:[1,0,1] neg_lo:[1,0,0] neg_hi:[1,0,0]
	v_and_b32_e32 v27, 0xffff0000, v69
	v_and_b32_e32 v26, 0xffff0000, v68
	global_load_dwordx4 v[66:69], v150, s[60:61]
	v_pk_fma_f32 v[148:149], v[2:3], v[0:1], v[70:71] op_sel_hi:[1,0,1] neg_lo:[1,0,0] neg_hi:[1,0,0]
	v_pk_fma_f32 v[140:141], v[8:9], v[0:1], v[72:73] op_sel_hi:[1,0,1] neg_lo:[1,0,0] neg_hi:[1,0,0]
	global_load_dwordx4 v[70:73], v150, s[60:61] offset:32
	v_lshlrev_b32_e32 v74, 16, v88
	v_and_b32_e32 v75, 0xffff0000, v88
	v_lshlrev_b32_e32 v88, 16, v76
	v_and_b32_e32 v89, 0xffff0000, v76
	v_lshlrev_b32_e32 v76, 16, v77
	v_and_b32_e32 v77, 0xffff0000, v77
	v_mov_b32_e32 v32, v31
	v_pk_fma_f32 v[154:155], v[6:7], v[0:1], v[74:75] op_sel_hi:[1,0,1] neg_lo:[1,0,0] neg_hi:[1,0,0]
	v_pk_fma_f32 v[152:153], v[12:13], v[0:1], v[76:77] op_sel_hi:[1,0,1] neg_lo:[1,0,0] neg_hi:[1,0,0]
	global_load_dwordx4 v[74:77], v150, s[60:61] offset:64
	v_lshlrev_b32_e32 v94, 16, v82
	v_and_b32_e32 v95, 0xffff0000, v82
	v_lshlrev_b32_e32 v102, 16, v83
	v_and_b32_e32 v103, 0xffff0000, v83
	v_pk_fma_f32 v[82:83], v[32:33], v[0:1], v[26:27] op_sel_hi:[1,0,1] neg_lo:[1,0,0] neg_hi:[1,0,0]
	v_pk_fma_f32 v[112:113], v[4:5], v[0:1], v[112:113] op_sel_hi:[1,0,1] neg_lo:[1,0,0] neg_hi:[1,0,0]
	v_pk_mul_f32 v[26:27], v[82:83], v[82:83]
	global_load_dwordx4 v[2:5], v150, s[60:61] offset:128
	global_load_dwordx4 v[6:9], v150, s[60:61] offset:160
	v_pk_fma_f32 v[138:139], v[80:81], v[80:81], v[26:27]
	global_load_dwordx4 v[26:29], v150, s[60:61] offset:96
	v_pk_fma_f32 v[158:159], v[14:15], v[0:1], v[90:91] op_sel_hi:[1,0,1] neg_lo:[1,0,0] neg_hi:[1,0,0]
	v_pk_fma_f32 v[90:91], v[52:53], v[0:1], v[102:103] op_sel_hi:[1,0,1] neg_lo:[1,0,0] neg_hi:[1,0,0]
	v_pk_fma_f32 v[48:49], v[48:49], v[0:1], v[136:137] op_sel_hi:[1,0,1] neg_lo:[1,0,0] neg_hi:[1,0,0]
	v_pk_fma_f32 v[102:103], v[46:47], v[0:1], v[130:131] op_sel_hi:[1,0,1] neg_lo:[1,0,0] neg_hi:[1,0,0]
	v_pk_fma_f32 v[94:95], v[50:51], v[0:1], v[94:95] op_sel_hi:[1,0,1] neg_lo:[1,0,0] neg_hi:[1,0,0]
	v_pk_fma_f32 v[50:51], v[56:57], v[0:1], v[104:105] op_sel_hi:[1,0,1] neg_lo:[1,0,0] neg_hi:[1,0,0]
	v_mov_b32_e32 v104, v103
	v_mov_b32_e32 v105, v49
	v_mov_b32_e32 v46, v102
	v_mov_b32_e32 v47, v48
	v_pk_mul_f32 v[104:105], v[104:105], v[104:105]
	v_pk_fma_f32 v[156:157], v[10:11], v[0:1], v[88:89] op_sel_hi:[1,0,1] neg_lo:[1,0,0] neg_hi:[1,0,0]
	v_pk_fma_f32 v[88:89], v[16:17], v[0:1], v[106:107] op_sel_hi:[1,0,1] neg_lo:[1,0,0] neg_hi:[1,0,0]
	v_pk_fma_f32 v[46:47], v[46:47], v[46:47], v[104:105]
	v_pk_fma_f32 v[104:105], v[20:21], v[0:1], v[132:133] op_sel_hi:[1,0,1] neg_lo:[1,0,0] neg_hi:[1,0,0]
	v_pk_fma_f32 v[106:107], v[18:19], v[0:1], v[114:115] op_sel_hi:[1,0,1] neg_lo:[1,0,0] neg_hi:[1,0,0]
	v_pk_fma_f32 v[58:59], v[58:59], v[0:1], v[92:93] op_sel_hi:[1,0,1] neg_lo:[1,0,0] neg_hi:[1,0,0]
	v_pk_fma_f32 v[62:63], v[62:63], v[0:1], v[108:109] op_sel_hi:[1,0,1] neg_lo:[1,0,0] neg_hi:[1,0,0]
	v_pk_fma_f32 v[92:93], v[34:35], v[0:1], v[98:99] op_sel_hi:[1,0,1] neg_lo:[1,0,0] neg_hi:[1,0,0]
	v_pk_fma_f32 v[98:99], v[38:39], v[0:1], v[110:111] op_sel_hi:[1,0,1] neg_lo:[1,0,0] neg_hi:[1,0,0]
	v_mov_b32_e32 v20, v107
	v_mov_b32_e32 v21, v105
	v_pk_fma_f32 v[108:109], v[24:25], v[0:1], v[128:129] op_sel_hi:[1,0,1] neg_lo:[1,0,0] neg_hi:[1,0,0]
	v_pk_fma_f32 v[110:111], v[22:23], v[0:1], v[118:119] op_sel_hi:[1,0,1] neg_lo:[1,0,0] neg_hi:[1,0,0]
	v_mov_b32_e32 v18, v106
	v_mov_b32_e32 v19, v104
	v_pk_mul_f32 v[20:21], v[20:21], v[20:21]
	v_mov_b32_e32 v22, v111
	v_mov_b32_e32 v23, v109
	v_pk_mul_f32 v[160:161], v[112:113], v[112:113]
	v_pk_mul_f32 v[162:163], v[148:149], v[148:149]
	v_pk_fma_f32 v[18:19], v[18:19], v[18:19], v[20:21]
	v_mov_b32_e32 v20, v110
	v_mov_b32_e32 v21, v108
	v_pk_mul_f32 v[22:23], v[22:23], v[22:23]
	v_pk_mul_f32 v[166:167], v[154:155], v[154:155]
	v_pk_fma_f32 v[54:55], v[54:55], v[0:1], v[96:97] op_sel_hi:[1,0,1] neg_lo:[1,0,0] neg_hi:[1,0,0]
	v_pk_fma_f32 v[52:53], v[60:61], v[0:1], v[116:117] op_sel_hi:[1,0,1] neg_lo:[1,0,0] neg_hi:[1,0,0]
	v_pk_fma_f32 v[56:57], v[64:65], v[0:1], v[126:127] op_sel_hi:[1,0,1] neg_lo:[1,0,0] neg_hi:[1,0,0]
	v_pk_fma_f32 v[60:61], v[36:37], v[0:1], v[120:121] op_sel_hi:[1,0,1] neg_lo:[1,0,0] neg_hi:[1,0,0]
	v_pk_fma_f32 v[64:65], v[40:41], v[0:1], v[124:125] op_sel_hi:[1,0,1] neg_lo:[1,0,0] neg_hi:[1,0,0]
	v_pk_fma_f32 v[96:97], v[44:45], v[0:1], v[134:135] op_sel_hi:[1,0,1] neg_lo:[1,0,0] neg_hi:[1,0,0]
	v_pk_fma_f32 v[100:101], v[42:43], v[0:1], v[100:101] op_sel_hi:[1,0,1] neg_lo:[1,0,0] neg_hi:[1,0,0]
	v_pk_fma_f32 v[20:21], v[20:21], v[20:21], v[22:23]
	v_add_f32_e32 v0, v160, v161
	v_add_f32_e32 v22, v162, v163
	v_pk_mul_f32 v[164:165], v[140:141], v[140:141]
	v_add_f32_e32 v0, v22, v0
	v_add_f32_e32 v22, v166, v167
	v_pk_mul_f32 v[170:171], v[156:157], v[156:157]
	v_add_f32_e32 v0, v0, v22
	v_add_f32_e32 v22, v164, v165
	v_pk_mul_f32 v[168:169], v[152:153], v[152:153]
	v_add_f32_e32 v0, v0, v22
	v_add_f32_e32 v22, v170, v171
	v_pk_mul_f32 v[174:175], v[158:159], v[158:159]
	v_add_f32_e32 v0, v0, v22
	v_add_f32_e32 v22, v168, v169
	v_pk_mul_f32 v[172:173], v[88:89], v[88:89]
	v_add_f32_e32 v0, v0, v22
	v_add_f32_e32 v22, v174, v175
	v_pk_mul_f32 v[178:179], v[94:95], v[94:95]
	v_add_f32_e32 v0, v0, v22
	v_add_f32_e32 v22, v172, v173
	v_pk_mul_f32 v[176:177], v[90:91], v[90:91]
	v_add_f32_e32 v0, v0, v22
	v_add_f32_e32 v22, v178, v179
	v_pk_mul_f32 v[182:183], v[54:55], v[54:55]
	v_add_f32_e32 v0, v0, v22
	v_add_f32_e32 v22, v176, v177
	v_pk_mul_f32 v[180:181], v[50:51], v[50:51]
	v_add_f32_e32 v0, v0, v22
	v_add_f32_e32 v22, v182, v183
	v_pk_mul_f32 v[184:185], v[58:59], v[58:59]
	v_add_f32_e32 v0, v0, v22
	v_add_f32_e32 v22, v180, v181
	v_pk_mul_f32 v[116:117], v[52:53], v[52:53]
	v_add_f32_e32 v0, v0, v22
	v_add_f32_e32 v22, v184, v185
	v_pk_mul_f32 v[186:187], v[62:63], v[62:63]
	v_add_f32_e32 v0, v0, v22
	v_add_f32_e32 v22, v116, v117
	v_pk_mul_f32 v[126:127], v[56:57], v[56:57]
	v_add_f32_e32 v0, v0, v22
	v_add_f32_e32 v22, v186, v187
	v_pk_mul_f32 v[34:35], v[92:93], v[92:93]
	v_add_f32_e32 v0, v0, v22
	v_add_f32_e32 v22, v126, v127
	v_pk_mul_f32 v[36:37], v[60:61], v[60:61]
	v_add_f32_e32 v0, v0, v22
	v_add_f32_e32 v22, v34, v35
	v_pk_mul_f32 v[38:39], v[98:99], v[98:99]
	v_add_f32_e32 v0, v0, v22
	v_add_f32_e32 v22, v36, v37
	v_pk_mul_f32 v[40:41], v[64:65], v[64:65]
	v_add_f32_e32 v0, v0, v22
	v_add_f32_e32 v22, v38, v39
	v_pk_mul_f32 v[42:43], v[100:101], v[100:101]
	v_add_f32_e32 v0, v0, v22
	v_add_f32_e32 v22, v40, v41
	v_pk_mul_f32 v[44:45], v[96:97], v[96:97]
	v_add_f32_e32 v0, v0, v22
	v_add_f32_e32 v22, v42, v43
	v_add_f32_e32 v0, v0, v22
	v_add_f32_e32 v22, v44, v45
	v_add_f32_e32 v0, v0, v22
	v_add_f32_e32 v0, v0, v46
	v_add_f32_e32 v0, v0, v47
	v_add_f32_e32 v0, v0, v18
	v_add_f32_e32 v0, v0, v19
	v_add_f32_e32 v0, v0, v20
	v_add_f32_e32 v0, v0, v21
	v_add_f32_e32 v0, v0, v122
	v_add_f32_e32 v0, v0, v123
	v_add_f32_e32 v0, v0, v138
	v_add_f32_e32 v18, v0, v139
	ds_bpermute_b32 v19, v190, v18
	global_load_dwordx4 v[10:13], v150, s[60:61] offset:192
	global_load_dwordx4 v[14:17], v150, s[60:61] offset:224
	v_lshlrev_b32_e32 v0, 3, v189
	v_lshl_add_u64 v[46:47], v[78:79], 0, v[0:1]
	s_waitcnt lgkmcnt(0)
	v_add_f32_e32 v0, v18, v19
	v_fmamk_f32 v0, v0, 0x3c000000, v146
	v_cmp_gt_f32_e32 vcc, s54, v0
	v_mul_f32_e32 v18, 0x4b800000, v0
	global_load_dwordx4 v[30:33], v150, s[60:61] offset:256
	v_cndmask_b32_e32 v0, v0, v18, vcc
	v_rsq_f32_e32 v0, v0
	global_load_dwordx4 v[38:41], v150, s[60:61] offset:288
	global_load_dwordx4 v[22:25], v150, s[60:61] offset:320
	global_load_dwordx4 v[42:45], v150, s[60:61] offset:352
	global_load_dwordx4 v[34:37], v150, s[60:61] offset:384
	global_load_dwordx4 v[18:21], v150, s[60:61] offset:416
	v_mul_f32_e32 v78, 0x45800000, v0
	v_cndmask_b32_e32 v0, v0, v78, vcc
	v_mul_f32_e32 v0, 0x3f4ccccd, v0
	v_pk_mul_f32 v[78:79], v[148:149], v[0:1] op_sel_hi:[1,0]
	s_waitcnt vmcnt(13)
	v_pk_mul_f32 v[66:67], v[66:67], v[78:79]
	v_pk_mul_f32 v[78:79], v[112:113], v[0:1] op_sel_hi:[1,0]
	v_cvt_pk_bf16_f32 v220, v66, v67
	v_pk_mul_f32 v[68:69], v[68:69], v[78:79]
	s_nop 0
	v_mbcnt_lo_u32_b32 v236, -1, 0
	v_mbcnt_hi_u32_b32 v236, -1, v236
	v_and_b32_e32 v236, 32, v236
	v_lshrrev_b32_e32 v236, 2, v236
	v_mov_b32_e32 v237, 0
	v_lshl_add_u64 v[46:47], v[46:47], 0, v[236:237]
	v_cvt_pk_bf16_f32 v221, v68, v69
	v_pk_mul_f32 v[66:67], v[154:155], v[0:1] op_sel_hi:[1,0]
	v_pk_mul_f32 v[68:69], v[140:141], v[0:1] op_sel_hi:[1,0]
	s_waitcnt vmcnt(12)
	v_pk_mul_f32 v[66:67], v[70:71], v[66:67]
	v_pk_mul_f32 v[68:69], v[72:73], v[68:69]
	v_cvt_pk_bf16_f32 v222, v66, v67
	v_cvt_pk_bf16_f32 v223, v68, v69
	s_nop 1
	v_permlane32_swap_b32_e32 v220, v222
	v_permlane32_swap_b32_e32 v221, v223
	global_store_dwordx4 v[46:47], v[220:223], off
	v_pk_mul_f32 v[66:67], v[156:157], v[0:1] op_sel_hi:[1,0]
	v_pk_mul_f32 v[68:69], v[152:153], v[0:1] op_sel_hi:[1,0]
	s_waitcnt vmcnt(12)
	v_pk_mul_f32 v[66:67], v[74:75], v[66:67]
	v_pk_mul_f32 v[68:69], v[76:77], v[68:69]
	v_cvt_pk_bf16_f32 v224, v66, v67
	v_cvt_pk_bf16_f32 v225, v68, v69
	v_pk_mul_f32 v[66:67], v[158:159], v[0:1] op_sel_hi:[1,0]
	v_pk_mul_f32 v[70:71], v[88:89], v[0:1] op_sel_hi:[1,0]
	s_waitcnt vmcnt(9)
	v_pk_mul_f32 v[26:27], v[66:67], v[26:27]
	global_load_dwordx4 v[66:69], v150, s[60:61] offset:448
	v_pk_mul_f32 v[28:29], v[70:71], v[28:29]
	v_cvt_pk_bf16_f32 v226, v26, v27
	v_cvt_pk_bf16_f32 v227, v28, v29
	s_nop 1
	v_permlane32_swap_b32_e32 v224, v226
	v_permlane32_swap_b32_e32 v225, v227
	global_store_dwordx4 v[46:47], v[224:227], off offset:32
	v_pk_mul_f32 v[26:27], v[94:95], v[0:1] op_sel_hi:[1,0]
	v_pk_mul_f32 v[70:71], v[90:91], v[0:1] op_sel_hi:[1,0]
	v_pk_mul_f32 v[2:3], v[26:27], v[2:3]
	global_load_dwordx4 v[26:29], v150, s[60:61] offset:480
	v_pk_mul_f32 v[4:5], v[70:71], v[4:5]
	v_cvt_pk_bf16_f32 v228, v2, v3
	v_cvt_pk_bf16_f32 v229, v4, v5
	v_pk_mul_f32 v[2:3], v[54:55], v[0:1] op_sel_hi:[1,0]
	v_pk_mul_f32 v[4:5], v[50:51], v[0:1] op_sel_hi:[1,0]
	v_pk_mul_f32 v[2:3], v[2:3], v[6:7]
	v_pk_mul_f32 v[4:5], v[4:5], v[8:9]
	v_cvt_pk_bf16_f32 v230, v2, v3
	v_cvt_pk_bf16_f32 v231, v4, v5
	s_nop 1
	v_permlane32_swap_b32_e32 v228, v230
	v_permlane32_swap_b32_e32 v229, v231
	global_store_dwordx4 v[46:47], v[228:231], off offset:64
	v_pk_mul_f32 v[2:3], v[58:59], v[0:1] op_sel_hi:[1,0]
	v_pk_mul_f32 v[4:5], v[52:53], v[0:1] op_sel_hi:[1,0]
	s_waitcnt vmcnt(12)
	v_pk_mul_f32 v[2:3], v[2:3], v[10:11]
	v_pk_mul_f32 v[4:5], v[4:5], v[12:13]
	v_cvt_pk_bf16_f32 v232, v2, v3
	v_cvt_pk_bf16_f32 v233, v4, v5
	v_pk_mul_f32 v[2:3], v[62:63], v[0:1] op_sel_hi:[1,0]
	v_pk_mul_f32 v[4:5], v[56:57], v[0:1] op_sel_hi:[1,0]
	s_waitcnt vmcnt(11)
	v_pk_mul_f32 v[2:3], v[2:3], v[14:15]
	v_pk_mul_f32 v[4:5], v[4:5], v[16:17]
	v_cvt_pk_bf16_f32 v234, v2, v3
	v_cvt_pk_bf16_f32 v235, v4, v5
	s_nop 1
	v_permlane32_swap_b32_e32 v232, v234
	v_permlane32_swap_b32_e32 v233, v235
	global_store_dwordx4 v[46:47], v[232:235], off offset:96
	v_pk_mul_f32 v[2:3], v[92:93], v[0:1] op_sel_hi:[1,0]
	v_pk_mul_f32 v[4:5], v[60:61], v[0:1] op_sel_hi:[1,0]
	s_waitcnt vmcnt(11)
	v_pk_mul_f32 v[2:3], v[2:3], v[30:31]
	v_pk_mul_f32 v[4:5], v[4:5], v[32:33]
	v_cvt_pk_bf16_f32 v220, v2, v3
	v_cvt_pk_bf16_f32 v221, v4, v5
	v_pk_mul_f32 v[2:3], v[98:99], v[0:1] op_sel_hi:[1,0]
	v_pk_mul_f32 v[4:5], v[64:65], v[0:1] op_sel_hi:[1,0]
	s_waitcnt vmcnt(10)
	v_pk_mul_f32 v[2:3], v[2:3], v[38:39]
	v_pk_mul_f32 v[4:5], v[4:5], v[40:41]
	v_cvt_pk_bf16_f32 v222, v2, v3
	v_cvt_pk_bf16_f32 v223, v4, v5
	s_nop 1
	v_permlane32_swap_b32_e32 v220, v222
	v_permlane32_swap_b32_e32 v221, v223
	global_store_dwordx4 v[46:47], v[220:223], off offset:128
	v_pk_mul_f32 v[2:3], v[100:101], v[0:1] op_sel_hi:[1,0]
	v_pk_mul_f32 v[4:5], v[96:97], v[0:1] op_sel_hi:[1,0]
	s_waitcnt vmcnt(10)
	v_pk_mul_f32 v[2:3], v[2:3], v[22:23]
	v_pk_mul_f32 v[4:5], v[4:5], v[24:25]
	v_cvt_pk_bf16_f32 v224, v2, v3
	v_cvt_pk_bf16_f32 v225, v4, v5
	v_pk_mul_f32 v[2:3], v[102:103], v[0:1] op_sel_hi:[1,0]
	v_pk_mul_f32 v[4:5], v[48:49], v[0:1] op_sel_hi:[1,0]
	s_waitcnt vmcnt(9)
	v_pk_mul_f32 v[2:3], v[2:3], v[42:43]
	v_pk_mul_f32 v[4:5], v[4:5], v[44:45]
	v_cvt_pk_bf16_f32 v226, v2, v3
	v_cvt_pk_bf16_f32 v227, v4, v5
	s_nop 1
	v_permlane32_swap_b32_e32 v224, v226
	v_permlane32_swap_b32_e32 v225, v227
	global_store_dwordx4 v[46:47], v[224:227], off offset:160
	v_pk_mul_f32 v[2:3], v[106:107], v[0:1] op_sel_hi:[1,0]
	v_pk_mul_f32 v[4:5], v[104:105], v[0:1] op_sel_hi:[1,0]
	s_waitcnt vmcnt(9)
	v_pk_mul_f32 v[2:3], v[2:3], v[34:35]
	v_pk_mul_f32 v[4:5], v[4:5], v[36:37]
	v_cvt_pk_bf16_f32 v228, v2, v3
	v_cvt_pk_bf16_f32 v229, v4, v5
	v_pk_mul_f32 v[2:3], v[110:111], v[0:1] op_sel_hi:[1,0]
	v_pk_mul_f32 v[4:5], v[108:109], v[0:1] op_sel_hi:[1,0]
	s_waitcnt vmcnt(8)
	v_pk_mul_f32 v[2:3], v[2:3], v[18:19]
	v_pk_mul_f32 v[4:5], v[4:5], v[20:21]
	v_cvt_pk_bf16_f32 v230, v2, v3
	v_cvt_pk_bf16_f32 v231, v4, v5
	s_nop 1
	v_permlane32_swap_b32_e32 v228, v230
	v_permlane32_swap_b32_e32 v229, v231
	global_store_dwordx4 v[46:47], v[228:231], off offset:192
	v_mov_b32_e32 v2, v84
	v_mov_b32_e32 v3, v86
	v_mov_b32_e32 v86, v85
	v_pk_mul_f32 v[2:3], v[2:3], v[0:1] op_sel_hi:[1,0]
	v_pk_mul_f32 v[4:5], v[86:87], v[0:1] op_sel_hi:[1,0]
	s_waitcnt vmcnt(5)
	v_pk_mul_f32 v[2:3], v[2:3], v[66:67]
	v_pk_mul_f32 v[4:5], v[4:5], v[68:69]
	v_cvt_pk_bf16_f32 v232, v2, v3
	v_cvt_pk_bf16_f32 v233, v4, v5
	v_mov_b32_e32 v2, v80
	v_mov_b32_e32 v3, v82
	v_mov_b32_e32 v82, v81
	v_pk_mul_f32 v[2:3], v[2:3], v[0:1] op_sel_hi:[1,0]
	v_pk_mul_f32 v[4:5], v[82:83], v[0:1] op_sel_hi:[1,0]
	s_waitcnt vmcnt(3)
	v_pk_mul_f32 v[2:3], v[2:3], v[26:27]
	v_pk_mul_f32 v[4:5], v[4:5], v[28:29]
	v_cvt_pk_bf16_f32 v234, v2, v3
	v_cvt_pk_bf16_f32 v235, v4, v5
	s_nop 1
	v_permlane32_swap_b32_e32 v232, v234
	v_permlane32_swap_b32_e32 v233, v235
	global_store_dwordx4 v[46:47], v[232:235], off offset:224
	s_load_dword s0, s[84:85], 0x10
	s_waitcnt lgkmcnt(0)
	s_lshr_b32 s0, s0, 16
	s_cmp_lg_u32 s0, 0
	s_cselect_b64 s[0:1], -1, 0
	s_cmp_lg_u64 s[0:1], 0
	v_readlane_b32 s0, v244, 0
	s_addc_u32 s2, s2, s0
	s_cmpk_gt_i32 s2, 0x4ff
	v_readlane_b32 s1, v244, 1
	s_cbranch_scc1 .LBB0_466
